# barrier poll loops without the sleep between polls
# baseline (speedup 1.0000x reference)
; __device__ __forceinline__ void fast_grid_barrier(unsigned* base, int seam, int tid) {
;     ...
;         else { unsigned sp = 0; while (__hip_atomic_load(flg, __ATOMIC_RELAXED, __HIP_MEMORY_SCOPE_AGENT) == 0u) { __builtin_amdgcn_s_sleep(2); if (++sp > (1u << 22)) break; } }
.Lsm1_wtop_loop:
	global_load_dword v1, v0, s[6:7] offset:2176 sc1
	s_waitcnt vmcnt(0)
	v_cmp_le_u32_e32 vcc, s4, v1
	s_cbranch_vccnz .Lsm1_topdone
	s_sleep 0
	s_add_i32 s3, s3, -1
	s_cmp_lg_u32 s3, 0
	s_cbranch_scc1 .Lsm1_wtop_loop

; __device__ __forceinline__ void fast_grid_barrier(unsigned* base, int seam, int tid) {
;     asm volatile("s_waitcnt vmcnt(0)" ::: "memory");
;     __syncthreads();
;     if (tid == 0) {
;         unsigned* cnt = base + seam * 128;
;         unsigned* flg = cnt + 64;
;         __builtin_amdgcn_fence(__ATOMIC_RELEASE, "agent");
;         asm volatile("s_waitcnt vmcnt(0)" ::: "memory");
;         const unsigned old = __hip_atomic_fetch_add(cnt, 1u, __ATOMIC_RELAXED, __HIP_MEMORY_SCOPE_AGENT);
;         if (old == gridDim.x - 1) __hip_atomic_store(flg, 1u, __ATOMIC_RELAXED, __HIP_MEMORY_SCOPE_AGENT);
;         else { unsigned sp = 0; while (__hip_atomic_load(flg, __ATOMIC_RELAXED, __HIP_MEMORY_SCOPE_AGENT) == 0u) { __builtin_amdgcn_s_sleep(2); if (++sp > (1u << 22)) break; } }
;         __builtin_amdgcn_fence(__ATOMIC_ACQUIRE, "agent");
;         asm volatile("s_waitcnt vmcnt(0)" ::: "memory");
;     }
;     __syncthreads();
; }
.Lsm3_early:
	s_mul_i32 s3, s99, 2
	v_cmp_eq_u32_e32 vcc, s3, v1
	s_cbranch_vccnz .Lsm3_ewb
	s_branch .Lsm3_wtop

; __device__ __forceinline__ void fast_grid_barrier(unsigned* base, int seam, int tid) {
;     asm volatile("s_waitcnt vmcnt(0)" ::: "memory");
;     __syncthreads();
;     if (tid == 0) {
;         unsigned* cnt = base + seam * 128;
;         unsigned* flg = cnt + 64;
;         __builtin_amdgcn_fence(__ATOMIC_RELEASE, "agent");
;         asm volatile("s_waitcnt vmcnt(0)" ::: "memory");
;         const unsigned old = __hip_atomic_fetch_add(cnt, 1u, __ATOMIC_RELAXED, __HIP_MEMORY_SCOPE_AGENT);
;         if (old == gridDim.x - 1) __hip_atomic_store(flg, 1u, __ATOMIC_RELAXED, __HIP_MEMORY_SCOPE_AGENT);
;         else { unsigned sp = 0; while (__hip_atomic_load(flg, __ATOMIC_RELAXED, __HIP_MEMORY_SCOPE_AGENT) == 0u) { __builtin_amdgcn_s_sleep(2); if (++sp > (1u << 22)) break; } }
;         __builtin_amdgcn_fence(__ATOMIC_ACQUIRE, "agent");
;         asm volatile("s_waitcnt vmcnt(0)" ::: "memory");
;     }
;     __syncthreads();
; }
.Lsm7_early:
	s_mul_i32 s3, s99, 6
	v_cmp_eq_u32_e32 vcc, s3, v1
	s_cbranch_vccnz .Lsm7_ewb
	s_branch .Lsm7_wtop
